# v6 plus removal of the back-to-back s_setprio 0/1 pairs inside the 32-MFMA blocks of the three GEMM K-loops
# baseline (speedup 1.0000x reference)
; #define PG8_STAGE(bufoff, gbase, voff) do { _Pragma("unroll") for (int _i = 0; _i < 2; ++_i) \
;         __builtin_amdgcn_global_load_lds((const unsigned*)((const char*)(gbase) + (voff)[_i]), (PG8_LAS unsigned*)(lds + (bufoff) + ldsw + _i * 8192), 16, 0, 0); } while (0)
; #define PG8_LDA(dst, b, h) do { _Pragma("unroll") for (int m = 0; m < 4; ++m) _Pragma("unroll") for (int k = 0; k < 2; ++k) dst[m][k] = *(const PG8_LAS bf16x8*)(lds + PG8_SA(b, h) + aoff + m * 2048 + k * 1024); } while (0)
; #define PG8_LDB(dst, b, h) do { _Pragma("unroll") for (int n = 0; n < 2; ++n) _Pragma("unroll") for (int k = 0; k < 2; ++k) dst[n][k] = *(const PG8_LAS bf16x8*)(lds + PG8_SB(b, h) + boff + n * 2048 + k * 1024); } while (0)
; #define PG8_MMA(ai, bj, At, Bt) do { __builtin_amdgcn_s_setprio(1); _Pragma("unroll") for (int m = 0; m < 4; ++m) _Pragma("unroll") for (int n = 0; n < 2; ++n) _Pragma("unroll") for (int k = 0; k < 2; ++k) \
;         acc[ai][bj][m][n] = __builtin_amdgcn_mfma_f32_16x16x32_bf16(Bt[n][k], At[m][k], acc[ai][bj][m][n], 0, 0, 0); __builtin_amdgcn_s_setprio(0); } while (0)
; #define PG8_WAIT_V(n) asm volatile("s_waitcnt vmcnt(" #n ")" ::: "memory")
; template <class Epi, class Sched, bool ALIGN_EPI = false, bool SP2 = false>
; __device__ __forceinline__ void gemm_phase(PG8_LAS unsigned char* lds, const Gemm g, const Sched& S, const Epi& E) {
;     ...
;             PG8_LDB(B0, 0, 0); PG8_LDB(B1, 0, 1); PG8_SCHED; PG8_LDA(At, 0, 0); PG8_STAGE(PG8_SA(1, 1), a1 + hstep, voffA);
;             PG8_WAIT_V(8); PG8_WAIT_L(0); PG8_BAR; PG8_MMA(0, 0, At, B0); PG8_MMA(0, 1, At, B1); PG8_BAR; PG8_SCHED;
;             PG8_LDA(At, 0, 1); PG8_STAGE(PG8_SB(0, 0), b2, voffB); PG8_STAGE(PG8_SB(0, 1), b2 + hstep, voffB); PG8_STAGE(PG8_SA(0, 0), a2, voffA);
;             PG8_WAIT_V(8); PG8_WAIT_L(0); PG8_BAR; PG8_MMA(1, 0, At, B0); PG8_MMA(1, 1, At, B1); PG8_BAR; PG8_SCHED;
;             PG8_LDB(B0, 1, 0); PG8_LDB(B1, 1, 1); PG8_SCHED; PG8_LDA(At, 1, 0); PG8_STAGE(PG8_SA(0, 1), a2 + hstep, voffA);
;             PG8_WAIT_V(8); PG8_WAIT_L(0); PG8_BAR; PG8_MMA(0, 0, At, B0); PG8_MMA(0, 1, At, B1); PG8_BAR; PG8_SCHED;
;             PG8_LDA(At, 1, 1); PG8_STAGE(PG8_SB(1, 0), b3, voffB); PG8_STAGE(PG8_SB(1, 1), b3 + hstep, voffB); PG8_STAGE(PG8_SA(1, 0), a3, voffA);
;             PG8_WAIT_V(8); PG8_WAIT_L(0); PG8_BAR; PG8_MMA(1, 0, At, B0); PG8_MMA(1, 1, At, B1); PG8_BAR; PG8_SCHED;
.LBB0_143:
	ds_read_b128 v[130:133], v193
	ds_read_b128 v[134:137], v193 offset:1024
	ds_read_b128 v[138:141], v193 offset:2048
	ds_read_b128 v[142:145], v193 offset:3072
	ds_read_b128 v[166:169], v194
	ds_read_b128 v[170:173], v194 offset:1024
	ds_read_b128 v[174:177], v194 offset:2048
	ds_read_b128 v[178:181], v194 offset:3072
	s_add_u32 s90, s88, 0xfffc0080
	s_addc_u32 s91, s89, -1
	s_cmp_eq_u32 vcc_hi, 12
	s_cselect_b32 s93, s1, s91
	s_cselect_b32 s92, s11, s90
	s_cselect_b32 s91, s79, vcc_lo
	s_cselect_b32 s90, s81, s83
	v_lshl_add_u64 v[190:191], s[88:89], 0, v[156:157]
	s_add_i32 m0, s58, 0xc000
	ds_read_b128 v[182:185], v195
	ds_read_b128 v[186:189], v195 offset:1024
	ds_read_b128 v[200:203], v195 offset:2048
	ds_read_b128 v[204:207], v195 offset:3072
	ds_read_b128 v[208:211], v195 offset:4096
	ds_read_b128 v[212:215], v195 offset:5120
	ds_read_b128 v[216:219], v195 offset:6144
	ds_read_b128 v[220:223], v195 offset:7168
	global_load_lds_dwordx4 v[190:191], off
	v_lshl_add_u64 v[190:191], s[88:89], 0, v[158:159]
	s_add_i32 m0, s58, 0xe000
	s_nop 0
	global_load_lds_dwordx4 v[190:191], off
	s_waitcnt vmcnt(8)
	s_waitcnt lgkmcnt(0)
	s_barrier
	s_setprio 1
	s_waitcnt lgkmcnt(0)
	v_mfma_f32_16x16x32_bf16 v[126:129], v[130:133], v[182:185], v[126:129]
	v_mfma_f32_16x16x32_bf16 v[122:125], v[138:141], v[182:185], v[122:125]
	v_mfma_f32_16x16x32_bf16 v[110:113], v[130:133], v[200:203], v[110:113]
	v_mfma_f32_16x16x32_bf16 v[106:109], v[138:141], v[200:203], v[106:109]
	v_mfma_f32_16x16x32_bf16 v[94:97], v[130:133], v[208:211], v[94:97]
	v_mfma_f32_16x16x32_bf16 v[90:93], v[138:141], v[208:211], v[90:93]
	v_mfma_f32_16x16x32_bf16 v[78:81], v[130:133], v[216:219], v[78:81]
	v_mfma_f32_16x16x32_bf16 v[74:77], v[138:141], v[216:219], v[74:77]
	v_mfma_f32_16x16x32_bf16 v[126:129], v[134:137], v[186:189], v[126:129]
	v_mfma_f32_16x16x32_bf16 v[122:125], v[142:145], v[186:189], v[122:125]
	v_mfma_f32_16x16x32_bf16 v[110:113], v[134:137], v[204:207], v[110:113]
	v_mfma_f32_16x16x32_bf16 v[106:109], v[142:145], v[204:207], v[106:109]
	v_mfma_f32_16x16x32_bf16 v[94:97], v[134:137], v[212:215], v[94:97]
	v_mfma_f32_16x16x32_bf16 v[90:93], v[142:145], v[212:215], v[90:93]
	v_mfma_f32_16x16x32_bf16 v[78:81], v[134:137], v[220:223], v[78:81]
	v_mfma_f32_16x16x32_bf16 v[74:77], v[142:145], v[220:223], v[74:77]
	v_mfma_f32_16x16x32_bf16 v[118:121], v[166:169], v[182:185], v[118:121]
	v_mfma_f32_16x16x32_bf16 v[114:117], v[174:177], v[182:185], v[114:117]
	v_mfma_f32_16x16x32_bf16 v[102:105], v[166:169], v[200:203], v[102:105]
	v_mfma_f32_16x16x32_bf16 v[98:101], v[174:177], v[200:203], v[98:101]
	v_mfma_f32_16x16x32_bf16 v[86:89], v[166:169], v[208:211], v[86:89]
	v_mfma_f32_16x16x32_bf16 v[82:85], v[174:177], v[208:211], v[82:85]
	v_mfma_f32_16x16x32_bf16 v[70:73], v[166:169], v[216:219], v[70:73]
	v_mfma_f32_16x16x32_bf16 v[66:69], v[174:177], v[216:219], v[66:69]
	v_mfma_f32_16x16x32_bf16 v[118:121], v[170:173], v[186:189], v[118:121]
	v_mfma_f32_16x16x32_bf16 v[114:117], v[178:181], v[186:189], v[114:117]
	v_mfma_f32_16x16x32_bf16 v[102:105], v[170:173], v[204:207], v[102:105]
	v_mfma_f32_16x16x32_bf16 v[98:101], v[178:181], v[204:207], v[98:101]
	v_mfma_f32_16x16x32_bf16 v[86:89], v[170:173], v[212:215], v[86:89]
	v_mfma_f32_16x16x32_bf16 v[82:85], v[178:181], v[212:215], v[82:85]
	v_mfma_f32_16x16x32_bf16 v[70:73], v[170:173], v[220:223], v[70:73]
	v_mfma_f32_16x16x32_bf16 v[66:69], v[178:181], v[220:223], v[66:69]
	s_setprio 0
	s_barrier
	s_add_i32 s94, s7, s97
	v_lshl_add_u64 v[190:191], s[90:91], 0, v[148:149]
	s_mov_b32 m0, s94
	ds_read_b128 v[182:185], v195 offset:16384
	ds_read_b128 v[186:189], v195 offset:17408
	ds_read_b128 v[200:203], v195 offset:18432
	ds_read_b128 v[204:207], v195 offset:19456
	ds_read_b128 v[208:211], v195 offset:20480
	ds_read_b128 v[212:215], v195 offset:21504
	ds_read_b128 v[216:219], v195 offset:22528
	ds_read_b128 v[220:223], v195 offset:23552
	global_load_lds_dwordx4 v[190:191], off
	s_add_i32 m0, s94, 0x2000
	s_add_u32 s94, s90, 0x40000
	v_lshl_add_u64 v[224:225], s[90:91], 0, v[152:153]
	s_addc_u32 s95, s91, 0
	s_add_i32 s18, s64, s97
	global_load_lds_dwordx4 v[224:225], off
	v_lshl_add_u64 v[226:227], s[94:95], 0, v[148:149]
	s_mov_b32 m0, s18
	v_lshl_add_u64 v[228:229], s[92:93], 0, v[150:151]
	global_load_lds_dwordx4 v[226:227], off
	v_lshl_add_u64 v[226:227], s[94:95], 0, v[152:153]
	s_add_i32 m0, s18, 0x2000
	s_nop 0
	global_load_lds_dwordx4 v[226:227], off
	v_lshl_add_u64 v[226:227], s[92:93], 0, v[146:147]
	s_mov_b32 m0, s58
	s_nop 0
	global_load_lds_dwordx4 v[226:227], off
	s_mov_b32 m0, s59
	s_nop 0
	global_load_lds_dwordx4 v[228:229], off
	s_waitcnt vmcnt(8)
	s_waitcnt lgkmcnt(0)
	s_barrier
; #define PG8_STAGE(bufoff, gbase, voff) do { _Pragma("unroll") for (int _i = 0; _i < 2; ++_i) \
;         __builtin_amdgcn_global_load_lds((const unsigned*)((const char*)(gbase) + (voff)[_i]), (PG8_LAS unsigned*)(lds + (bufoff) + ldsw + _i * 8192), 16, 0, 0); } while (0)
; #define PG8_LDA(dst, b, h) do { _Pragma("unroll") for (int m = 0; m < 4; ++m) _Pragma("unroll") for (int k = 0; k < 2; ++k) dst[m][k] = *(const PG8_LAS bf16x8*)(lds + PG8_SA(b, h) + aoff + m * 2048 + k * 1024); } while (0)
; #define PG8_LDB(dst, b, h) do { _Pragma("unroll") for (int n = 0; n < 2; ++n) _Pragma("unroll") for (int k = 0; k < 2; ++k) dst[n][k] = *(const PG8_LAS bf16x8*)(lds + PG8_SB(b, h) + boff + n * 2048 + k * 1024); } while (0)
; #define PG8_MMA(ai, bj, At, Bt) do { __builtin_amdgcn_s_setprio(1); _Pragma("unroll") for (int m = 0; m < 4; ++m) _Pragma("unroll") for (int n = 0; n < 2; ++n) _Pragma("unroll") for (int k = 0; k < 2; ++k) \
;         acc[ai][bj][m][n] = __builtin_amdgcn_mfma_f32_16x16x32_bf16(Bt[n][k], At[m][k], acc[ai][bj][m][n], 0, 0, 0); __builtin_amdgcn_s_setprio(0); } while (0)
; #define PG8_WAIT_V(n) asm volatile("s_waitcnt vmcnt(" #n ")" ::: "memory")
; #define PG8_WAIT_L(n) asm volatile("s_waitcnt lgkmcnt(" #n ")" ::: "memory")
; #define PG8_BAR __builtin_amdgcn_s_barrier()
; #define PG8_SCHED __builtin_amdgcn_sched_barrier(0)
; template <class Epi, class Sched, bool ALIGN_EPI = false, bool SP2 = false>
; __device__ __forceinline__ void gemm_phase(PG8_LAS unsigned char* lds, const Gemm g, const Sched& S, const Epi& E) {
;     ...
;             PG8_LDB(B0, 0, 0); PG8_LDB(B1, 0, 1); PG8_SCHED; PG8_LDA(At, 0, 0); PG8_STAGE(PG8_SA(1, 1), a1 + hstep, voffA);
;             PG8_WAIT_V(8); PG8_WAIT_L(0); PG8_BAR; PG8_MMA(0, 0, At, B0); PG8_MMA(0, 1, At, B1); PG8_BAR; PG8_SCHED;
;             PG8_LDA(At, 0, 1); PG8_STAGE(PG8_SB(0, 0), b2, voffB); PG8_STAGE(PG8_SB(0, 1), b2 + hstep, voffB); PG8_STAGE(PG8_SA(0, 0), a2, voffA);
;             PG8_WAIT_V(8); PG8_WAIT_L(0); PG8_BAR; PG8_MMA(1, 0, At, B0); PG8_MMA(1, 1, At, B1); PG8_BAR; PG8_SCHED;
;             PG8_LDB(B0, 1, 0); PG8_LDB(B1, 1, 1); PG8_SCHED; PG8_LDA(At, 1, 0); PG8_STAGE(PG8_SA(0, 1), a2 + hstep, voffA);
;             PG8_WAIT_V(8); PG8_WAIT_L(0); PG8_BAR; PG8_MMA(0, 0, At, B0); PG8_MMA(0, 1, At, B1); PG8_BAR; PG8_SCHED;
	s_setprio 1
	s_waitcnt lgkmcnt(0)
	v_mfma_f32_16x16x32_bf16 v[62:65], v[130:133], v[182:185], v[62:65]
	v_mfma_f32_16x16x32_bf16 v[58:61], v[138:141], v[182:185], v[58:61]
	v_mfma_f32_16x16x32_bf16 v[46:49], v[130:133], v[200:203], v[46:49]
	v_mfma_f32_16x16x32_bf16 v[42:45], v[138:141], v[200:203], v[42:45]
	v_mfma_f32_16x16x32_bf16 v[30:33], v[130:133], v[208:211], v[30:33]
	v_mfma_f32_16x16x32_bf16 v[26:29], v[138:141], v[208:211], v[26:29]
	v_mfma_f32_16x16x32_bf16 v[14:17], v[130:133], v[216:219], v[14:17]
	v_mfma_f32_16x16x32_bf16 v[10:13], v[138:141], v[216:219], v[10:13]
	v_mfma_f32_16x16x32_bf16 v[62:65], v[134:137], v[186:189], v[62:65]
	v_mfma_f32_16x16x32_bf16 v[58:61], v[142:145], v[186:189], v[58:61]
	v_mfma_f32_16x16x32_bf16 v[46:49], v[134:137], v[204:207], v[46:49]
	v_mfma_f32_16x16x32_bf16 v[42:45], v[142:145], v[204:207], v[42:45]
	v_mfma_f32_16x16x32_bf16 v[30:33], v[134:137], v[212:215], v[30:33]
	v_mfma_f32_16x16x32_bf16 v[26:29], v[142:145], v[212:215], v[26:29]
	v_mfma_f32_16x16x32_bf16 v[14:17], v[134:137], v[220:223], v[14:17]
	v_mfma_f32_16x16x32_bf16 v[10:13], v[142:145], v[220:223], v[10:13]
	v_mfma_f32_16x16x32_bf16 v[54:57], v[166:169], v[182:185], v[54:57]
	v_mfma_f32_16x16x32_bf16 v[50:53], v[174:177], v[182:185], v[50:53]
	v_mfma_f32_16x16x32_bf16 v[38:41], v[166:169], v[200:203], v[38:41]
	v_mfma_f32_16x16x32_bf16 v[34:37], v[174:177], v[200:203], v[34:37]
	v_mfma_f32_16x16x32_bf16 v[22:25], v[166:169], v[208:211], v[22:25]
	v_mfma_f32_16x16x32_bf16 v[18:21], v[174:177], v[208:211], v[18:21]
	v_mfma_f32_16x16x32_bf16 v[6:9], v[166:169], v[216:219], v[6:9]
	v_mfma_f32_16x16x32_bf16 v[2:5], v[174:177], v[216:219], v[2:5]
	v_mfma_f32_16x16x32_bf16 v[54:57], v[170:173], v[186:189], v[54:57]
	v_mfma_f32_16x16x32_bf16 v[50:53], v[178:181], v[186:189], v[50:53]
	v_mfma_f32_16x16x32_bf16 v[38:41], v[170:173], v[204:207], v[38:41]
	v_mfma_f32_16x16x32_bf16 v[34:37], v[178:181], v[204:207], v[34:37]
	v_mfma_f32_16x16x32_bf16 v[22:25], v[170:173], v[212:215], v[22:25]
	v_mfma_f32_16x16x32_bf16 v[18:21], v[178:181], v[212:215], v[18:21]
	v_mfma_f32_16x16x32_bf16 v[6:9], v[170:173], v[220:223], v[6:9]
	v_mfma_f32_16x16x32_bf16 v[2:5], v[178:181], v[220:223], v[2:5]
	s_setprio 0
	s_barrier
	s_add_i32 s18, 0, 0x18000
	s_add_i32 s94, 0, 0x1c000
	v_add_u32_e32 v142, s18, v192
	v_add_u32_e32 v154, s94, v192
	ds_read_b128 v[130:133], v142
	ds_read_b128 v[134:137], v142 offset:1024
	ds_read_b128 v[138:141], v142 offset:2048
	ds_read_b128 v[142:145], v142 offset:3072
	ds_read_b128 v[166:169], v154
	ds_read_b128 v[170:173], v154 offset:1024
	ds_read_b128 v[174:177], v154 offset:2048
	ds_read_b128 v[178:181], v154 offset:3072
	s_add_u32 s92, s92, 0x40000
	s_addc_u32 s93, s93, 0
	s_mov_b32 m0, s56
	v_lshl_add_u64 v[230:231], s[92:93], 0, v[146:147]
	ds_read_b128 v[182:185], v195 offset:32768
	ds_read_b128 v[186:189], v195 offset:33792
	ds_read_b128 v[200:203], v195 offset:34816
	ds_read_b128 v[204:207], v195 offset:35840
	ds_read_b128 v[208:211], v195 offset:36864
	ds_read_b128 v[212:215], v195 offset:37888
	ds_read_b128 v[216:219], v195 offset:38912
	ds_read_b128 v[220:223], v195 offset:39936
	global_load_lds_dwordx4 v[230:231], off
	v_lshl_add_u64 v[230:231], s[92:93], 0, v[150:151]
	s_mov_b32 m0, s57
	s_nop 0
	global_load_lds_dwordx4 v[230:231], off
	s_waitcnt vmcnt(8)
	s_waitcnt lgkmcnt(0)
	s_barrier
	s_setprio 1
	s_waitcnt lgkmcnt(0)
	v_mfma_f32_16x16x32_bf16 v[126:129], v[130:133], v[182:185], v[126:129]
	v_mfma_f32_16x16x32_bf16 v[122:125], v[138:141], v[182:185], v[122:125]
	v_mfma_f32_16x16x32_bf16 v[110:113], v[130:133], v[200:203], v[110:113]
	v_mfma_f32_16x16x32_bf16 v[106:109], v[138:141], v[200:203], v[106:109]
	v_mfma_f32_16x16x32_bf16 v[94:97], v[130:133], v[208:211], v[94:97]
	v_mfma_f32_16x16x32_bf16 v[90:93], v[138:141], v[208:211], v[90:93]
	v_mfma_f32_16x16x32_bf16 v[78:81], v[130:133], v[216:219], v[78:81]
	v_mfma_f32_16x16x32_bf16 v[74:77], v[138:141], v[216:219], v[74:77]
	v_mfma_f32_16x16x32_bf16 v[126:129], v[134:137], v[186:189], v[126:129]
	v_mfma_f32_16x16x32_bf16 v[122:125], v[142:145], v[186:189], v[122:125]
	v_mfma_f32_16x16x32_bf16 v[110:113], v[134:137], v[204:207], v[110:113]
	v_mfma_f32_16x16x32_bf16 v[106:109], v[142:145], v[204:207], v[106:109]
	v_mfma_f32_16x16x32_bf16 v[94:97], v[134:137], v[212:215], v[94:97]
	v_mfma_f32_16x16x32_bf16 v[90:93], v[142:145], v[212:215], v[90:93]
	v_mfma_f32_16x16x32_bf16 v[78:81], v[134:137], v[220:223], v[78:81]
	v_mfma_f32_16x16x32_bf16 v[74:77], v[142:145], v[220:223], v[74:77]
	v_mfma_f32_16x16x32_bf16 v[118:121], v[166:169], v[182:185], v[118:121]
	v_mfma_f32_16x16x32_bf16 v[114:117], v[174:177], v[182:185], v[114:117]
	v_mfma_f32_16x16x32_bf16 v[102:105], v[166:169], v[200:203], v[102:105]
	v_mfma_f32_16x16x32_bf16 v[98:101], v[174:177], v[200:203], v[98:101]
	v_mfma_f32_16x16x32_bf16 v[86:89], v[166:169], v[208:211], v[86:89]
	v_mfma_f32_16x16x32_bf16 v[82:85], v[174:177], v[208:211], v[82:85]
	v_mfma_f32_16x16x32_bf16 v[70:73], v[166:169], v[216:219], v[70:73]
	v_mfma_f32_16x16x32_bf16 v[66:69], v[174:177], v[216:219], v[66:69]
	v_mfma_f32_16x16x32_bf16 v[118:121], v[170:173], v[186:189], v[118:121]
	v_mfma_f32_16x16x32_bf16 v[114:117], v[178:181], v[186:189], v[114:117]
	v_mfma_f32_16x16x32_bf16 v[102:105], v[170:173], v[204:207], v[102:105]
	v_mfma_f32_16x16x32_bf16 v[98:101], v[178:181], v[204:207], v[98:101]
	v_mfma_f32_16x16x32_bf16 v[86:89], v[170:173], v[212:215], v[86:89]
	v_mfma_f32_16x16x32_bf16 v[82:85], v[178:181], v[212:215], v[82:85]
	v_mfma_f32_16x16x32_bf16 v[70:73], v[170:173], v[220:223], v[70:73]
	v_mfma_f32_16x16x32_bf16 v[66:69], v[178:181], v[220:223], v[66:69]
	s_setprio 0
	s_barrier
; #define PG8_STAGE(bufoff, gbase, voff) do { _Pragma("unroll") for (int _i = 0; _i < 2; ++_i) \
;         __builtin_amdgcn_global_load_lds((const unsigned*)((const char*)(gbase) + (voff)[_i]), (PG8_LAS unsigned*)(lds + (bufoff) + ldsw + _i * 8192), 16, 0, 0); } while (0)
; #define PG8_LDA(dst, b, h) do { _Pragma("unroll") for (int m = 0; m < 4; ++m) _Pragma("unroll") for (int k = 0; k < 2; ++k) dst[m][k] = *(const PG8_LAS bf16x8*)(lds + PG8_SA(b, h) + aoff + m * 2048 + k * 1024); } while (0)
; #define PG8_MMA(ai, bj, At, Bt) do { __builtin_amdgcn_s_setprio(1); _Pragma("unroll") for (int m = 0; m < 4; ++m) _Pragma("unroll") for (int n = 0; n < 2; ++n) _Pragma("unroll") for (int k = 0; k < 2; ++k) \
;         acc[ai][bj][m][n] = __builtin_amdgcn_mfma_f32_16x16x32_bf16(Bt[n][k], At[m][k], acc[ai][bj][m][n], 0, 0, 0); __builtin_amdgcn_s_setprio(0); } while (0)
; #define PG8_WAIT_V(n) asm volatile("s_waitcnt vmcnt(" #n ")" ::: "memory")
; #define PG8_WAIT_L(n) asm volatile("s_waitcnt lgkmcnt(" #n ")" ::: "memory")
; #define PG8_BAR __builtin_amdgcn_s_barrier()
; #define PG8_SCHED __builtin_amdgcn_sched_barrier(0)
; template <class Epi, class Sched, bool ALIGN_EPI = false, bool SP2 = false>
; __device__ __forceinline__ void gemm_phase(PG8_LAS unsigned char* lds, const Gemm g, const Sched& S, const Epi& E) {
;     ...
;         for (int t = 0; t < nt; t += 2) {
;             if constexpr (Epi::HAS_MID) { if (t == nt / 2) E.mid(acc, cur, wr, wc, fr, fq); }
;             const bool last = (t == nt - 2);
;             const char* a1 = cA + (size_t)(t + 1) * kstep;
;             const char* a2 = last ? nA : cA + (size_t)(t + 2) * kstep; const char* b2 = last ? nB : cB + (size_t)(t + 2) * kstep;
;             const char* a3 = a2 + kstep; const char* b3 = b2 + kstep;
;     ...
;             PG8_LDA(At, 1, 1); PG8_STAGE(PG8_SB(1, 0), b3, voffB); PG8_STAGE(PG8_SB(1, 1), b3 + hstep, voffB); PG8_STAGE(PG8_SA(1, 0), a3, voffA);
;             PG8_WAIT_V(8); PG8_WAIT_L(0); PG8_BAR; PG8_MMA(1, 0, At, B0); PG8_MMA(1, 1, At, B1); PG8_BAR; PG8_SCHED;
	s_add_i32 s18, s18, s97
	v_lshl_add_u64 v[190:191], v[190:191], 0, s[74:75]
	s_mov_b32 m0, s18
	ds_read_b128 v[182:185], v195 offset:49152
	ds_read_b128 v[186:189], v195 offset:50176
	ds_read_b128 v[200:203], v195 offset:51200
	ds_read_b128 v[204:207], v195 offset:52224
	ds_read_b128 v[208:211], v195 offset:53248
	ds_read_b128 v[212:215], v195 offset:54272
	ds_read_b128 v[216:219], v195 offset:55296
	ds_read_b128 v[220:223], v195 offset:56320
	global_load_lds_dwordx4 v[190:191], off
	s_add_i32 m0, s18, 0x2000
	s_add_u32 s90, s90, 0x40080
	v_lshl_add_u64 v[190:191], v[224:225], 0, s[74:75]
	s_addc_u32 s91, s91, 0
	s_add_i32 s18, s94, s97
	global_load_lds_dwordx4 v[190:191], off
	v_lshl_add_u64 v[190:191], s[90:91], 0, v[148:149]
	s_mov_b32 m0, s18
	s_nop 0
	global_load_lds_dwordx4 v[190:191], off
	v_lshl_add_u64 v[190:191], s[90:91], 0, v[152:153]
	s_add_i32 m0, s18, 0x2000
	s_nop 0
	global_load_lds_dwordx4 v[190:191], off
	v_lshl_add_u64 v[190:191], v[226:227], 0, s[74:75]
	s_mov_b32 m0, s19
	s_nop 0
	global_load_lds_dwordx4 v[190:191], off
	v_lshl_add_u64 v[190:191], v[228:229], 0, s[74:75]
	s_mov_b32 m0, s66
	s_nop 0
	global_load_lds_dwordx4 v[190:191], off
	s_waitcnt vmcnt(8)
	s_waitcnt lgkmcnt(0)
	s_barrier
	s_setprio 1
	s_waitcnt lgkmcnt(0)
	v_mfma_f32_16x16x32_bf16 v[62:65], v[130:133], v[182:185], v[62:65]
	v_mfma_f32_16x16x32_bf16 v[58:61], v[138:141], v[182:185], v[58:61]
	v_mfma_f32_16x16x32_bf16 v[46:49], v[130:133], v[200:203], v[46:49]
	v_mfma_f32_16x16x32_bf16 v[42:45], v[138:141], v[200:203], v[42:45]
	v_mfma_f32_16x16x32_bf16 v[30:33], v[130:133], v[208:211], v[30:33]
	v_mfma_f32_16x16x32_bf16 v[26:29], v[138:141], v[208:211], v[26:29]
	v_mfma_f32_16x16x32_bf16 v[14:17], v[130:133], v[216:219], v[14:17]
	v_mfma_f32_16x16x32_bf16 v[10:13], v[138:141], v[216:219], v[10:13]
	v_mfma_f32_16x16x32_bf16 v[62:65], v[134:137], v[186:189], v[62:65]
	v_mfma_f32_16x16x32_bf16 v[58:61], v[142:145], v[186:189], v[58:61]
	v_mfma_f32_16x16x32_bf16 v[46:49], v[134:137], v[204:207], v[46:49]
	v_mfma_f32_16x16x32_bf16 v[42:45], v[142:145], v[204:207], v[42:45]
	v_mfma_f32_16x16x32_bf16 v[30:33], v[134:137], v[212:215], v[30:33]
	v_mfma_f32_16x16x32_bf16 v[26:29], v[142:145], v[212:215], v[26:29]
	v_mfma_f32_16x16x32_bf16 v[14:17], v[134:137], v[220:223], v[14:17]
	v_mfma_f32_16x16x32_bf16 v[10:13], v[142:145], v[220:223], v[10:13]
	v_mfma_f32_16x16x32_bf16 v[54:57], v[166:169], v[182:185], v[54:57]
	v_mfma_f32_16x16x32_bf16 v[50:53], v[174:177], v[182:185], v[50:53]
	v_mfma_f32_16x16x32_bf16 v[38:41], v[166:169], v[200:203], v[38:41]
	v_mfma_f32_16x16x32_bf16 v[34:37], v[174:177], v[200:203], v[34:37]
	v_mfma_f32_16x16x32_bf16 v[22:25], v[166:169], v[208:211], v[22:25]
	v_mfma_f32_16x16x32_bf16 v[18:21], v[174:177], v[208:211], v[18:21]
	v_mfma_f32_16x16x32_bf16 v[6:9], v[166:169], v[216:219], v[6:9]
	v_mfma_f32_16x16x32_bf16 v[2:5], v[174:177], v[216:219], v[2:5]
	v_mfma_f32_16x16x32_bf16 v[54:57], v[170:173], v[186:189], v[54:57]
	v_mfma_f32_16x16x32_bf16 v[50:53], v[178:181], v[186:189], v[50:53]
	v_mfma_f32_16x16x32_bf16 v[38:41], v[170:173], v[204:207], v[38:41]
	v_mfma_f32_16x16x32_bf16 v[34:37], v[178:181], v[204:207], v[34:37]
	v_mfma_f32_16x16x32_bf16 v[22:25], v[170:173], v[212:215], v[22:25]
	v_mfma_f32_16x16x32_bf16 v[18:21], v[178:181], v[212:215], v[18:21]
	v_mfma_f32_16x16x32_bf16 v[6:9], v[170:173], v[220:223], v[6:9]
	v_mfma_f32_16x16x32_bf16 v[2:5], v[178:181], v[220:223], v[2:5]
	s_setprio 0
	s_barrier
	s_add_i32 vcc_hi, vcc_hi, 2
	s_add_u32 s88, s88, 0x100
	s_addc_u32 s89, s89, 0
	s_add_u32 s83, s83, 0x100
	s_addc_u32 vcc_lo, vcc_lo, 0
	s_cmp_gt_u32 vcc_hi, 13
	s_cbranch_scc0 .LBB0_143
	s_and_b64 vcc, exec, s[76:77]
	s_cbranch_vccz .LBB0_146
	s_barrier

; #define PG8_STAGE(bufoff, gbase, voff) do { _Pragma("unroll") for (int _i = 0; _i < 2; ++_i) \
;         __builtin_amdgcn_global_load_lds((const unsigned*)((const char*)(gbase) + (voff)[_i]), (PG8_LAS unsigned*)(lds + (bufoff) + ldsw + _i * 8192), 16, 0, 0); } while (0)
; #define PG8_LDA(dst, b, h) do { _Pragma("unroll") for (int m = 0; m < 4; ++m) _Pragma("unroll") for (int k = 0; k < 2; ++k) dst[m][k] = *(const PG8_LAS bf16x8*)(lds + PG8_SA(b, h) + aoff + m * 2048 + k * 1024); } while (0)
; #define PG8_LDB(dst, b, h) do { _Pragma("unroll") for (int n = 0; n < 2; ++n) _Pragma("unroll") for (int k = 0; k < 2; ++k) dst[n][k] = *(const PG8_LAS bf16x8*)(lds + PG8_SB(b, h) + boff + n * 2048 + k * 1024); } while (0)
; #define PG8_MMA(ai, bj, At, Bt) do { __builtin_amdgcn_s_setprio(1); _Pragma("unroll") for (int m = 0; m < 4; ++m) _Pragma("unroll") for (int n = 0; n < 2; ++n) _Pragma("unroll") for (int k = 0; k < 2; ++k) \
;         acc[ai][bj][m][n] = __builtin_amdgcn_mfma_f32_16x16x32_bf16(Bt[n][k], At[m][k], acc[ai][bj][m][n], 0, 0, 0); __builtin_amdgcn_s_setprio(0); } while (0)
; #define PG8_WAIT_V(n) asm volatile("s_waitcnt vmcnt(" #n ")" ::: "memory")
; #define PG8_WAIT_L(n) asm volatile("s_waitcnt lgkmcnt(" #n ")" ::: "memory")
; #define PG8_BAR __builtin_amdgcn_s_barrier()
; #define PG8_SCHED __builtin_amdgcn_sched_barrier(0)
; template <class Epi, class Sched, bool ALIGN_EPI = false, bool SP2 = false>
; __device__ __forceinline__ void gemm_phase(PG8_LAS unsigned char* lds, const Gemm g, const Sched& S, const Epi& E) {
;     ...
;             PG8_LDB(B0, 0, 0); PG8_LDB(B1, 0, 1); PG8_SCHED; PG8_LDA(At, 0, 0); PG8_STAGE(PG8_SA(1, 1), a1 + hstep, voffA);
;             PG8_WAIT_V(8); PG8_WAIT_L(0); PG8_BAR; PG8_MMA(0, 0, At, B0); PG8_MMA(0, 1, At, B1); PG8_BAR; PG8_SCHED;
;             PG8_LDA(At, 0, 1); PG8_STAGE(PG8_SB(0, 0), b2, voffB); PG8_STAGE(PG8_SB(0, 1), b2 + hstep, voffB); PG8_STAGE(PG8_SA(0, 0), a2, voffA);
.LBB0_587:
	s_add_u32 s2, s46, s60
	s_addc_u32 s62, s47, s61
	s_add_u32 s2, s2, 0x100
	s_addc_u32 s62, s62, 0
	s_add_u32 s95, s92, s60
	s_addc_u32 s63, s93, s61
	s_add_i32 s96, 0, 0x10000
	v_add_u32_e32 v3, s96, v209
	ds_read_b128 v[134:137], v3
	ds_read_b128 v[138:141], v3 offset:1024
	ds_read_b128 v[142:145], v3 offset:2048
	ds_read_b128 v[146:149], v3 offset:3072
	v_add_u32_e32 v3, s88, v209
	ds_read_b128 v[150:153], v3
	ds_read_b128 v[154:157], v3 offset:1024
	ds_read_b128 v[158:161], v3 offset:2048
	ds_read_b128 v[162:165], v3 offset:3072
	s_cmpk_eq_i32 s60, 0x700
	s_cselect_b32 s65, s29, s62
	s_cselect_b32 s64, s90, s2
	s_cselect_b32 s63, s31, s63
	s_cselect_b32 s62, s91, s95
	v_lshl_add_u64 v[4:5], v[204:205], 0, s[60:61]
	s_add_i32 m0, s59, 0xc000
	ds_read_b128 v[166:169], v210
	ds_read_b128 v[170:173], v210 offset:1024
	ds_read_b128 v[174:177], v210 offset:2048
	ds_read_b128 v[178:181], v210 offset:3072
	ds_read_b128 v[182:185], v210 offset:4096
	ds_read_b128 v[186:189], v210 offset:5120
	ds_read_b128 v[212:215], v210 offset:6144
	ds_read_b128 v[216:219], v210 offset:7168
	global_load_lds_dwordx4 v[4:5], off
	v_lshl_add_u64 v[4:5], v[206:207], 0, s[60:61]
	s_add_i32 m0, s59, 0xe000
	s_nop 0
	global_load_lds_dwordx4 v[4:5], off
	s_waitcnt vmcnt(8)
	s_waitcnt lgkmcnt(0)
	s_barrier
	s_setprio 1
	s_waitcnt lgkmcnt(0)
	v_mfma_f32_16x16x32_bf16 v[130:133], v[134:137], v[166:169], v[130:133]
	v_mfma_f32_16x16x32_bf16 v[126:129], v[142:145], v[166:169], v[126:129]
	v_mfma_f32_16x16x32_bf16 v[114:117], v[134:137], v[174:177], v[114:117]
	v_mfma_f32_16x16x32_bf16 v[110:113], v[142:145], v[174:177], v[110:113]
	v_mfma_f32_16x16x32_bf16 v[98:101], v[134:137], v[182:185], v[98:101]
	v_mfma_f32_16x16x32_bf16 v[94:97], v[142:145], v[182:185], v[94:97]
	v_mfma_f32_16x16x32_bf16 v[82:85], v[134:137], v[212:215], v[82:85]
	v_mfma_f32_16x16x32_bf16 v[78:81], v[142:145], v[212:215], v[78:81]
	v_mfma_f32_16x16x32_bf16 v[130:133], v[138:141], v[170:173], v[130:133]
	v_mfma_f32_16x16x32_bf16 v[126:129], v[146:149], v[170:173], v[126:129]
	v_mfma_f32_16x16x32_bf16 v[114:117], v[138:141], v[178:181], v[114:117]
	v_mfma_f32_16x16x32_bf16 v[110:113], v[146:149], v[178:181], v[110:113]
	v_mfma_f32_16x16x32_bf16 v[98:101], v[138:141], v[186:189], v[98:101]
	v_mfma_f32_16x16x32_bf16 v[94:97], v[146:149], v[186:189], v[94:97]
	v_mfma_f32_16x16x32_bf16 v[82:85], v[138:141], v[216:219], v[82:85]
	v_mfma_f32_16x16x32_bf16 v[78:81], v[146:149], v[216:219], v[78:81]
	v_mfma_f32_16x16x32_bf16 v[122:125], v[150:153], v[166:169], v[122:125]
	v_mfma_f32_16x16x32_bf16 v[118:121], v[158:161], v[166:169], v[118:121]
	v_mfma_f32_16x16x32_bf16 v[106:109], v[150:153], v[174:177], v[106:109]
	v_mfma_f32_16x16x32_bf16 v[102:105], v[158:161], v[174:177], v[102:105]
	v_mfma_f32_16x16x32_bf16 v[90:93], v[150:153], v[182:185], v[90:93]
	v_mfma_f32_16x16x32_bf16 v[86:89], v[158:161], v[182:185], v[86:89]
	v_mfma_f32_16x16x32_bf16 v[74:77], v[150:153], v[212:215], v[74:77]
	v_mfma_f32_16x16x32_bf16 v[70:73], v[158:161], v[212:215], v[70:73]
	v_mfma_f32_16x16x32_bf16 v[122:125], v[154:157], v[170:173], v[122:125]
	v_mfma_f32_16x16x32_bf16 v[118:121], v[162:165], v[170:173], v[118:121]
	v_mfma_f32_16x16x32_bf16 v[106:109], v[154:157], v[178:181], v[106:109]
	v_mfma_f32_16x16x32_bf16 v[102:105], v[162:165], v[178:181], v[102:105]
	v_mfma_f32_16x16x32_bf16 v[90:93], v[154:157], v[186:189], v[90:93]
	v_mfma_f32_16x16x32_bf16 v[86:89], v[162:165], v[186:189], v[86:89]
	v_mfma_f32_16x16x32_bf16 v[74:77], v[154:157], v[216:219], v[74:77]
	v_mfma_f32_16x16x32_bf16 v[70:73], v[162:165], v[216:219], v[70:73]
	s_setprio 0
	s_barrier
	s_add_i32 s2, s96, s58
	v_lshl_add_u64 v[220:221], s[62:63], 0, v[192:193]
	s_mov_b32 m0, s2
	ds_read_b128 v[166:169], v210 offset:16384
	ds_read_b128 v[170:173], v210 offset:17408
	ds_read_b128 v[174:177], v210 offset:18432
	ds_read_b128 v[178:181], v210 offset:19456
	ds_read_b128 v[182:185], v210 offset:20480
	ds_read_b128 v[186:189], v210 offset:21504
	ds_read_b128 v[212:215], v210 offset:22528
	ds_read_b128 v[216:219], v210 offset:23552
	global_load_lds_dwordx4 v[220:221], off
	s_add_i32 m0, s2, 0x2000
	s_add_u32 s96, s62, 0x40000
	v_lshl_add_u64 v[222:223], s[62:63], 0, v[196:197]
	s_addc_u32 s97, s63, 0
	s_add_i32 s2, s88, s58
	global_load_lds_dwordx4 v[222:223], off
	v_lshl_add_u64 v[4:5], s[96:97], 0, v[192:193]
	s_mov_b32 m0, s2
	v_lshl_add_u64 v[224:225], s[64:65], 0, v[190:191]
	global_load_lds_dwordx4 v[4:5], off
	v_lshl_add_u64 v[4:5], s[96:97], 0, v[196:197]
	s_add_i32 m0, s2, 0x2000
	v_lshl_add_u64 v[226:227], s[64:65], 0, v[194:195]
	global_load_lds_dwordx4 v[4:5], off
	s_mov_b32 m0, s59
	s_nop 0
	global_load_lds_dwordx4 v[224:225], off
	s_mov_b32 m0, s66
	s_nop 0
	global_load_lds_dwordx4 v[226:227], off
	s_waitcnt vmcnt(8)
	s_waitcnt lgkmcnt(0)
	s_barrier
; #define PG8_STAGE(bufoff, gbase, voff) do { _Pragma("unroll") for (int _i = 0; _i < 2; ++_i) \
;         __builtin_amdgcn_global_load_lds((const unsigned*)((const char*)(gbase) + (voff)[_i]), (PG8_LAS unsigned*)(lds + (bufoff) + ldsw + _i * 8192), 16, 0, 0); } while (0)
; #define PG8_LDA(dst, b, h) do { _Pragma("unroll") for (int m = 0; m < 4; ++m) _Pragma("unroll") for (int k = 0; k < 2; ++k) dst[m][k] = *(const PG8_LAS bf16x8*)(lds + PG8_SA(b, h) + aoff + m * 2048 + k * 1024); } while (0)
; #define PG8_LDB(dst, b, h) do { _Pragma("unroll") for (int n = 0; n < 2; ++n) _Pragma("unroll") for (int k = 0; k < 2; ++k) dst[n][k] = *(const PG8_LAS bf16x8*)(lds + PG8_SB(b, h) + boff + n * 2048 + k * 1024); } while (0)
; #define PG8_MMA(ai, bj, At, Bt) do { __builtin_amdgcn_s_setprio(1); _Pragma("unroll") for (int m = 0; m < 4; ++m) _Pragma("unroll") for (int n = 0; n < 2; ++n) _Pragma("unroll") for (int k = 0; k < 2; ++k) \
;         acc[ai][bj][m][n] = __builtin_amdgcn_mfma_f32_16x16x32_bf16(Bt[n][k], At[m][k], acc[ai][bj][m][n], 0, 0, 0); __builtin_amdgcn_s_setprio(0); } while (0)
; #define PG8_WAIT_V(n) asm volatile("s_waitcnt vmcnt(" #n ")" ::: "memory")
; #define PG8_WAIT_L(n) asm volatile("s_waitcnt lgkmcnt(" #n ")" ::: "memory")
; #define PG8_BAR __builtin_amdgcn_s_barrier()
; #define PG8_SCHED __builtin_amdgcn_sched_barrier(0)
; template <class Epi, class Sched, bool ALIGN_EPI = false, bool SP2 = false>
; __device__ __forceinline__ void gemm_phase(PG8_LAS unsigned char* lds, const Gemm g, const Sched& S, const Epi& E) {
;     ...
;             PG8_LDA(At, 0, 1); PG8_STAGE(PG8_SB(0, 0), b2, voffB); PG8_STAGE(PG8_SB(0, 1), b2 + hstep, voffB); PG8_STAGE(PG8_SA(0, 0), a2, voffA);
;             PG8_WAIT_V(8); PG8_WAIT_L(0); PG8_BAR; PG8_MMA(1, 0, At, B0); PG8_MMA(1, 1, At, B1); PG8_BAR; PG8_SCHED;
;             PG8_LDB(B0, 1, 0); PG8_LDB(B1, 1, 1); PG8_SCHED; PG8_LDA(At, 1, 0); PG8_STAGE(PG8_SA(0, 1), a2 + hstep, voffA);
;             PG8_WAIT_V(8); PG8_WAIT_L(0); PG8_BAR; PG8_MMA(0, 0, At, B0); PG8_MMA(0, 1, At, B1); PG8_BAR; PG8_SCHED;
	s_setprio 1
	s_waitcnt lgkmcnt(0)
	v_mfma_f32_16x16x32_bf16 v[66:69], v[134:137], v[166:169], v[66:69]
	v_mfma_f32_16x16x32_bf16 v[62:65], v[142:145], v[166:169], v[62:65]
	v_mfma_f32_16x16x32_bf16 v[50:53], v[134:137], v[174:177], v[50:53]
	v_mfma_f32_16x16x32_bf16 v[46:49], v[142:145], v[174:177], v[46:49]
	v_mfma_f32_16x16x32_bf16 v[34:37], v[134:137], v[182:185], v[34:37]
	v_mfma_f32_16x16x32_bf16 v[30:33], v[142:145], v[182:185], v[30:33]
	v_mfma_f32_16x16x32_bf16 v[18:21], v[134:137], v[212:215], v[18:21]
	v_mfma_f32_16x16x32_bf16 v[14:17], v[142:145], v[212:215], v[14:17]
	v_mfma_f32_16x16x32_bf16 v[66:69], v[138:141], v[170:173], v[66:69]
	v_mfma_f32_16x16x32_bf16 v[62:65], v[146:149], v[170:173], v[62:65]
	v_mfma_f32_16x16x32_bf16 v[50:53], v[138:141], v[178:181], v[50:53]
	v_mfma_f32_16x16x32_bf16 v[46:49], v[146:149], v[178:181], v[46:49]
	v_mfma_f32_16x16x32_bf16 v[34:37], v[138:141], v[186:189], v[34:37]
	v_mfma_f32_16x16x32_bf16 v[30:33], v[146:149], v[186:189], v[30:33]
	v_mfma_f32_16x16x32_bf16 v[18:21], v[138:141], v[216:219], v[18:21]
	v_mfma_f32_16x16x32_bf16 v[14:17], v[146:149], v[216:219], v[14:17]
	v_mfma_f32_16x16x32_bf16 v[58:61], v[150:153], v[166:169], v[58:61]
	v_mfma_f32_16x16x32_bf16 v[54:57], v[158:161], v[166:169], v[54:57]
	v_mfma_f32_16x16x32_bf16 v[42:45], v[150:153], v[174:177], v[42:45]
	v_mfma_f32_16x16x32_bf16 v[38:41], v[158:161], v[174:177], v[38:41]
	v_mfma_f32_16x16x32_bf16 v[26:29], v[150:153], v[182:185], v[26:29]
	v_mfma_f32_16x16x32_bf16 v[22:25], v[158:161], v[182:185], v[22:25]
	v_mfma_f32_16x16x32_bf16 v[10:13], v[150:153], v[212:215], v[10:13]
	v_mfma_f32_16x16x32_bf16 v[4:7], v[158:161], v[212:215], v[6:9]
	v_mfma_f32_16x16x32_bf16 v[58:61], v[154:157], v[170:173], v[58:61]
	v_mfma_f32_16x16x32_bf16 v[54:57], v[162:165], v[170:173], v[54:57]
	v_mfma_f32_16x16x32_bf16 v[42:45], v[154:157], v[178:181], v[42:45]
	v_mfma_f32_16x16x32_bf16 v[38:41], v[162:165], v[178:181], v[38:41]
	v_mfma_f32_16x16x32_bf16 v[26:29], v[154:157], v[186:189], v[26:29]
	v_mfma_f32_16x16x32_bf16 v[22:25], v[162:165], v[186:189], v[22:25]
	v_mfma_f32_16x16x32_bf16 v[10:13], v[154:157], v[216:219], v[10:13]
	v_mfma_f32_16x16x32_bf16 v[4:7], v[162:165], v[216:219], v[4:7]
	s_setprio 0
	s_barrier
	s_add_i32 s2, 0, 0x18000
	v_add_u32_e32 v3, s2, v209
	s_add_i32 s95, 0, 0x1c000
	ds_read_b128 v[134:137], v3
	ds_read_b128 v[138:141], v3 offset:1024
	ds_read_b128 v[142:145], v3 offset:2048
	ds_read_b128 v[146:149], v3 offset:3072
	v_add_u32_e32 v3, s95, v209
	ds_read_b128 v[150:153], v3
	ds_read_b128 v[154:157], v3 offset:1024
	ds_read_b128 v[158:161], v3 offset:2048
	ds_read_b128 v[162:165], v3 offset:3072
	s_add_u32 s64, s64, 0x40000
	s_addc_u32 s65, s65, 0
	s_mov_b32 m0, s67
	v_lshl_add_u64 v[8:9], s[64:65], 0, v[190:191]
	ds_read_b128 v[166:169], v210 offset:32768
	ds_read_b128 v[170:173], v210 offset:33792
	ds_read_b128 v[174:177], v210 offset:34816
	ds_read_b128 v[178:181], v210 offset:35840
	ds_read_b128 v[182:185], v210 offset:36864
	ds_read_b128 v[186:189], v210 offset:37888
	ds_read_b128 v[212:215], v210 offset:38912
	ds_read_b128 v[216:219], v210 offset:39936
	global_load_lds_dwordx4 v[8:9], off
	v_lshl_add_u64 v[8:9], s[64:65], 0, v[194:195]
	s_mov_b32 m0, s68
	s_nop 0
	global_load_lds_dwordx4 v[8:9], off
	s_waitcnt vmcnt(8)
	s_waitcnt lgkmcnt(0)
	s_barrier
	s_setprio 1
	s_waitcnt lgkmcnt(0)
	v_mfma_f32_16x16x32_bf16 v[130:133], v[134:137], v[166:169], v[130:133]
	v_mfma_f32_16x16x32_bf16 v[126:129], v[142:145], v[166:169], v[126:129]
	v_mfma_f32_16x16x32_bf16 v[114:117], v[134:137], v[174:177], v[114:117]
	v_mfma_f32_16x16x32_bf16 v[110:113], v[142:145], v[174:177], v[110:113]
	v_mfma_f32_16x16x32_bf16 v[98:101], v[134:137], v[182:185], v[98:101]
	v_mfma_f32_16x16x32_bf16 v[94:97], v[142:145], v[182:185], v[94:97]
	v_mfma_f32_16x16x32_bf16 v[82:85], v[134:137], v[212:215], v[82:85]
	v_mfma_f32_16x16x32_bf16 v[78:81], v[142:145], v[212:215], v[78:81]
	v_mfma_f32_16x16x32_bf16 v[130:133], v[138:141], v[170:173], v[130:133]
	v_mfma_f32_16x16x32_bf16 v[126:129], v[146:149], v[170:173], v[126:129]
	v_mfma_f32_16x16x32_bf16 v[114:117], v[138:141], v[178:181], v[114:117]
	v_mfma_f32_16x16x32_bf16 v[110:113], v[146:149], v[178:181], v[110:113]
	v_mfma_f32_16x16x32_bf16 v[98:101], v[138:141], v[186:189], v[98:101]
	v_mfma_f32_16x16x32_bf16 v[94:97], v[146:149], v[186:189], v[94:97]
	v_mfma_f32_16x16x32_bf16 v[82:85], v[138:141], v[216:219], v[82:85]
	v_mfma_f32_16x16x32_bf16 v[78:81], v[146:149], v[216:219], v[78:81]
	v_mfma_f32_16x16x32_bf16 v[122:125], v[150:153], v[166:169], v[122:125]
	v_mfma_f32_16x16x32_bf16 v[118:121], v[158:161], v[166:169], v[118:121]
	v_mfma_f32_16x16x32_bf16 v[106:109], v[150:153], v[174:177], v[106:109]
	v_mfma_f32_16x16x32_bf16 v[102:105], v[158:161], v[174:177], v[102:105]
	v_mfma_f32_16x16x32_bf16 v[90:93], v[150:153], v[182:185], v[90:93]
	v_mfma_f32_16x16x32_bf16 v[86:89], v[158:161], v[182:185], v[86:89]
	v_mfma_f32_16x16x32_bf16 v[74:77], v[150:153], v[212:215], v[74:77]
	v_mfma_f32_16x16x32_bf16 v[70:73], v[158:161], v[212:215], v[70:73]
	v_mfma_f32_16x16x32_bf16 v[122:125], v[154:157], v[170:173], v[122:125]
	v_mfma_f32_16x16x32_bf16 v[118:121], v[162:165], v[170:173], v[118:121]
	v_mfma_f32_16x16x32_bf16 v[106:109], v[154:157], v[178:181], v[106:109]
	v_mfma_f32_16x16x32_bf16 v[102:105], v[162:165], v[178:181], v[102:105]
	v_mfma_f32_16x16x32_bf16 v[90:93], v[154:157], v[186:189], v[90:93]
	v_mfma_f32_16x16x32_bf16 v[86:89], v[162:165], v[186:189], v[86:89]
	v_mfma_f32_16x16x32_bf16 v[74:77], v[154:157], v[216:219], v[74:77]
	v_mfma_f32_16x16x32_bf16 v[70:73], v[162:165], v[216:219], v[70:73]
	s_setprio 0
	s_barrier
; #define PG8_STAGE(bufoff, gbase, voff) do { _Pragma("unroll") for (int _i = 0; _i < 2; ++_i) \
;         __builtin_amdgcn_global_load_lds((const unsigned*)((const char*)(gbase) + (voff)[_i]), (PG8_LAS unsigned*)(lds + (bufoff) + ldsw + _i * 8192), 16, 0, 0); } while (0)
; #define PG8_LDA(dst, b, h) do { _Pragma("unroll") for (int m = 0; m < 4; ++m) _Pragma("unroll") for (int k = 0; k < 2; ++k) dst[m][k] = *(const PG8_LAS bf16x8*)(lds + PG8_SA(b, h) + aoff + m * 2048 + k * 1024); } while (0)
; #define PG8_MMA(ai, bj, At, Bt) do { __builtin_amdgcn_s_setprio(1); _Pragma("unroll") for (int m = 0; m < 4; ++m) _Pragma("unroll") for (int n = 0; n < 2; ++n) _Pragma("unroll") for (int k = 0; k < 2; ++k) \
;         acc[ai][bj][m][n] = __builtin_amdgcn_mfma_f32_16x16x32_bf16(Bt[n][k], At[m][k], acc[ai][bj][m][n], 0, 0, 0); __builtin_amdgcn_s_setprio(0); } while (0)
; #define PG8_WAIT_V(n) asm volatile("s_waitcnt vmcnt(" #n ")" ::: "memory")
; #define PG8_WAIT_L(n) asm volatile("s_waitcnt lgkmcnt(" #n ")" ::: "memory")
; #define PG8_BAR __builtin_amdgcn_s_barrier()
; #define PG8_SCHED __builtin_amdgcn_sched_barrier(0)
; template <class Epi, class Sched, bool ALIGN_EPI = false, bool SP2 = false>
; __device__ __forceinline__ void gemm_phase(PG8_LAS unsigned char* lds, const Gemm g, const Sched& S, const Epi& E) {
;     ...
;         for (int t = 0; t < nt; t += 2) {
;             if constexpr (Epi::HAS_MID) { if (t == nt / 2) E.mid(acc, cur, wr, wc, fr, fq); }
;             const bool last = (t == nt - 2);
;             const char* a1 = cA + (size_t)(t + 1) * kstep;
;             const char* a2 = last ? nA : cA + (size_t)(t + 2) * kstep; const char* b2 = last ? nB : cB + (size_t)(t + 2) * kstep;
;             const char* a3 = a2 + kstep; const char* b3 = b2 + kstep;
;     ...
;             PG8_LDA(At, 1, 1); PG8_STAGE(PG8_SB(1, 0), b3, voffB); PG8_STAGE(PG8_SB(1, 1), b3 + hstep, voffB); PG8_STAGE(PG8_SA(1, 0), a3, voffA);
;             PG8_WAIT_V(8); PG8_WAIT_L(0); PG8_BAR; PG8_MMA(1, 0, At, B0); PG8_MMA(1, 1, At, B1); PG8_BAR; PG8_SCHED;
	s_add_i32 s2, s2, s58
	v_lshl_add_u64 v[8:9], v[220:221], 0, s[22:23]
	s_mov_b32 m0, s2
	ds_read_b128 v[166:169], v210 offset:49152
	ds_read_b128 v[170:173], v210 offset:50176
	ds_read_b128 v[174:177], v210 offset:51200
	ds_read_b128 v[178:181], v210 offset:52224
	ds_read_b128 v[182:185], v210 offset:53248
	ds_read_b128 v[186:189], v210 offset:54272
	ds_read_b128 v[212:215], v210 offset:55296
	ds_read_b128 v[216:219], v210 offset:56320
	global_load_lds_dwordx4 v[8:9], off
	s_add_i32 m0, s2, 0x2000
	s_add_u32 s62, s62, 0x40080
	v_lshl_add_u64 v[8:9], v[222:223], 0, s[22:23]
	s_addc_u32 s63, s63, 0
	s_add_i32 s2, s95, s58
	global_load_lds_dwordx4 v[8:9], off
	v_lshl_add_u64 v[8:9], s[62:63], 0, v[192:193]
	s_mov_b32 m0, s2
	s_nop 0
	global_load_lds_dwordx4 v[8:9], off
	v_lshl_add_u64 v[8:9], s[62:63], 0, v[196:197]
	s_add_i32 m0, s2, 0x2000
	s_nop 0
	global_load_lds_dwordx4 v[8:9], off
	v_lshl_add_u64 v[8:9], v[224:225], 0, s[22:23]
	s_mov_b32 m0, s72
	s_nop 0
	global_load_lds_dwordx4 v[8:9], off
	v_lshl_add_u64 v[8:9], v[226:227], 0, s[22:23]
	s_mov_b32 m0, s73
	s_nop 0
	global_load_lds_dwordx4 v[8:9], off
	s_waitcnt vmcnt(8)
	s_waitcnt lgkmcnt(0)
	s_barrier
	s_setprio 1
	s_waitcnt lgkmcnt(0)
	v_mfma_f32_16x16x32_bf16 v[66:69], v[134:137], v[166:169], v[66:69]
	v_mfma_f32_16x16x32_bf16 v[62:65], v[142:145], v[166:169], v[62:65]
	v_mfma_f32_16x16x32_bf16 v[50:53], v[134:137], v[174:177], v[50:53]
	v_mfma_f32_16x16x32_bf16 v[46:49], v[142:145], v[174:177], v[46:49]
	v_mfma_f32_16x16x32_bf16 v[34:37], v[134:137], v[182:185], v[34:37]
	v_mfma_f32_16x16x32_bf16 v[30:33], v[142:145], v[182:185], v[30:33]
	v_mfma_f32_16x16x32_bf16 v[18:21], v[134:137], v[212:215], v[18:21]
	v_mfma_f32_16x16x32_bf16 v[14:17], v[142:145], v[212:215], v[14:17]
	v_mfma_f32_16x16x32_bf16 v[66:69], v[138:141], v[170:173], v[66:69]
	v_mfma_f32_16x16x32_bf16 v[62:65], v[146:149], v[170:173], v[62:65]
	v_mfma_f32_16x16x32_bf16 v[50:53], v[138:141], v[178:181], v[50:53]
	v_mfma_f32_16x16x32_bf16 v[46:49], v[146:149], v[178:181], v[46:49]
	v_mfma_f32_16x16x32_bf16 v[34:37], v[138:141], v[186:189], v[34:37]
	v_mfma_f32_16x16x32_bf16 v[30:33], v[146:149], v[186:189], v[30:33]
	v_mfma_f32_16x16x32_bf16 v[18:21], v[138:141], v[216:219], v[18:21]
	v_mfma_f32_16x16x32_bf16 v[14:17], v[146:149], v[216:219], v[14:17]
	v_mfma_f32_16x16x32_bf16 v[58:61], v[150:153], v[166:169], v[58:61]
	v_mfma_f32_16x16x32_bf16 v[54:57], v[158:161], v[166:169], v[54:57]
	v_mfma_f32_16x16x32_bf16 v[42:45], v[150:153], v[174:177], v[42:45]
	v_mfma_f32_16x16x32_bf16 v[38:41], v[158:161], v[174:177], v[38:41]
	v_mfma_f32_16x16x32_bf16 v[26:29], v[150:153], v[182:185], v[26:29]
	v_mfma_f32_16x16x32_bf16 v[22:25], v[158:161], v[182:185], v[22:25]
	v_mfma_f32_16x16x32_bf16 v[8:11], v[150:153], v[212:215], v[10:13]
	v_mfma_f32_16x16x32_bf16 v[4:7], v[158:161], v[212:215], v[4:7]
	v_mfma_f32_16x16x32_bf16 v[58:61], v[154:157], v[170:173], v[58:61]
	v_mfma_f32_16x16x32_bf16 v[54:57], v[162:165], v[170:173], v[54:57]
	v_mfma_f32_16x16x32_bf16 v[42:45], v[154:157], v[178:181], v[42:45]
	v_mfma_f32_16x16x32_bf16 v[38:41], v[162:165], v[178:181], v[38:41]
	v_mfma_f32_16x16x32_bf16 v[26:29], v[154:157], v[186:189], v[26:29]
	v_mfma_f32_16x16x32_bf16 v[22:25], v[162:165], v[186:189], v[22:25]
	v_mfma_f32_16x16x32_bf16 v[10:13], v[154:157], v[216:219], v[8:11]
	v_mfma_f32_16x16x32_bf16 v[6:9], v[162:165], v[216:219], v[4:7]
	s_setprio 0
	s_barrier
	s_add_i32 s94, s94, 2
	s_add_u32 s60, s60, 0x100
	s_addc_u32 s61, s61, 0
	s_cmp_gt_u32 s94, 13
	s_cbranch_scc1 .LBB0_590

; #define PG8_STAGE(bufoff, gbase, voff) do { _Pragma("unroll") for (int _i = 0; _i < 2; ++_i) \
;         __builtin_amdgcn_global_load_lds((const unsigned*)((const char*)(gbase) + (voff)[_i]), (PG8_LAS unsigned*)(lds + (bufoff) + ldsw + _i * 8192), 16, 0, 0); } while (0)
; #define PG8_LDA(dst, b, h) do { _Pragma("unroll") for (int m = 0; m < 4; ++m) _Pragma("unroll") for (int k = 0; k < 2; ++k) dst[m][k] = *(const PG8_LAS bf16x8*)(lds + PG8_SA(b, h) + aoff + m * 2048 + k * 1024); } while (0)
; #define PG8_LDB(dst, b, h) do { _Pragma("unroll") for (int n = 0; n < 2; ++n) _Pragma("unroll") for (int k = 0; k < 2; ++k) dst[n][k] = *(const PG8_LAS bf16x8*)(lds + PG8_SB(b, h) + boff + n * 2048 + k * 1024); } while (0)
; #define PG8_MMA(ai, bj, At, Bt) do { __builtin_amdgcn_s_setprio(1); _Pragma("unroll") for (int m = 0; m < 4; ++m) _Pragma("unroll") for (int n = 0; n < 2; ++n) _Pragma("unroll") for (int k = 0; k < 2; ++k) \
;         acc[ai][bj][m][n] = __builtin_amdgcn_mfma_f32_16x16x32_bf16(Bt[n][k], At[m][k], acc[ai][bj][m][n], 0, 0, 0); __builtin_amdgcn_s_setprio(0); } while (0)
; #define PG8_WAIT_V(n) asm volatile("s_waitcnt vmcnt(" #n ")" ::: "memory")
; #define PG8_WAIT_L(n) asm volatile("s_waitcnt lgkmcnt(" #n ")" ::: "memory")
; #define PG8_BAR __builtin_amdgcn_s_barrier()
; #define PG8_SCHED __builtin_amdgcn_sched_barrier(0)
; template <class Epi, class Sched, bool ALIGN_EPI = false, bool SP2 = false>
; __device__ __forceinline__ void gemm_phase(PG8_LAS unsigned char* lds, const Gemm g, const Sched& S, const Epi& E) {
;     ...
;             PG8_LDB(B0, 0, 0); PG8_LDB(B1, 0, 1); PG8_SCHED; PG8_LDA(At, 0, 0); PG8_STAGE(PG8_SA(1, 1), a1 + hstep, voffA);
;             PG8_WAIT_V(8); PG8_WAIT_L(0); PG8_BAR; PG8_MMA(0, 0, At, B0); PG8_MMA(0, 1, At, B1); PG8_BAR; PG8_SCHED;
;             PG8_LDA(At, 0, 1); PG8_STAGE(PG8_SB(0, 0), b2, voffB); PG8_STAGE(PG8_SB(0, 1), b2 + hstep, voffB); PG8_STAGE(PG8_SA(0, 0), a2, voffA);
.LBB0_722:
	v_add_u32_e32 v140, s74, v138
	ds_read_b128 v[144:147], v140
	ds_read_b128 v[148:151], v140 offset:1024
	ds_read_b128 v[152:155], v140 offset:2048
	ds_read_b128 v[156:159], v140 offset:3072
	v_add_u32_e32 v140, s75, v138
	ds_read_b128 v[160:163], v140
	ds_read_b128 v[164:167], v140 offset:1024
	ds_read_b128 v[168:171], v140 offset:2048
	ds_read_b128 v[172:175], v140 offset:3072
	s_add_u32 s2, s48, 0xfffc0080
	s_addc_u32 s46, s49, -1
	s_cmp_eq_u32 s80, 12
	s_cselect_b32 s53, s29, s46
	s_cselect_b32 s52, s31, s2
	s_cselect_b32 s47, s39, s79
	s_cselect_b32 s46, s77, s78
	v_lshl_add_u64 v[140:141], s[48:49], 0, v[0:1]
	s_add_i32 m0, s64, 0xc000
	ds_read_b128 v[176:179], v139
	ds_read_b128 v[180:183], v139 offset:1024
	ds_read_b128 v[184:187], v139 offset:2048
	ds_read_b128 v[188:191], v139 offset:3072
	ds_read_b128 v[192:195], v139 offset:4096
	ds_read_b128 v[196:199], v139 offset:5120
	ds_read_b128 v[200:203], v139 offset:6144
	ds_read_b128 v[204:207], v139 offset:7168
	global_load_lds_dwordx4 v[140:141], off
	v_lshl_add_u64 v[140:141], s[48:49], 0, v[134:135]
	s_add_i32 m0, s64, 0xe000
	s_nop 0
	global_load_lds_dwordx4 v[140:141], off
	s_waitcnt vmcnt(12)
	s_waitcnt lgkmcnt(0)
	s_barrier
	s_setprio 1
	s_waitcnt lgkmcnt(0)
	v_mfma_f32_16x16x32_bf16 v[2:5], v[144:147], v[176:179], v[2:5]
	v_mfma_f32_16x16x32_bf16 v[6:9], v[152:155], v[176:179], v[6:9]
	v_mfma_f32_16x16x32_bf16 v[22:25], v[144:147], v[184:187], v[22:25]
	v_mfma_f32_16x16x32_bf16 v[18:21], v[152:155], v[184:187], v[18:21]
	v_mfma_f32_16x16x32_bf16 v[38:41], v[144:147], v[192:195], v[38:41]
	v_mfma_f32_16x16x32_bf16 v[34:37], v[152:155], v[192:195], v[34:37]
	v_mfma_f32_16x16x32_bf16 v[54:57], v[144:147], v[200:203], v[54:57]
	v_mfma_f32_16x16x32_bf16 v[50:53], v[152:155], v[200:203], v[50:53]
	v_mfma_f32_16x16x32_bf16 v[2:5], v[148:151], v[180:183], v[2:5]
	v_mfma_f32_16x16x32_bf16 v[6:9], v[156:159], v[180:183], v[6:9]
	v_mfma_f32_16x16x32_bf16 v[22:25], v[148:151], v[188:191], v[22:25]
	v_mfma_f32_16x16x32_bf16 v[18:21], v[156:159], v[188:191], v[18:21]
	v_mfma_f32_16x16x32_bf16 v[38:41], v[148:151], v[196:199], v[38:41]
	v_mfma_f32_16x16x32_bf16 v[34:37], v[156:159], v[196:199], v[34:37]
	v_mfma_f32_16x16x32_bf16 v[54:57], v[148:151], v[204:207], v[54:57]
	v_mfma_f32_16x16x32_bf16 v[50:53], v[156:159], v[204:207], v[50:53]
	v_mfma_f32_16x16x32_bf16 v[10:13], v[160:163], v[176:179], v[10:13]
	v_mfma_f32_16x16x32_bf16 v[14:17], v[168:171], v[176:179], v[14:17]
	v_mfma_f32_16x16x32_bf16 v[26:29], v[160:163], v[184:187], v[26:29]
	v_mfma_f32_16x16x32_bf16 v[30:33], v[168:171], v[184:187], v[30:33]
	v_mfma_f32_16x16x32_bf16 v[42:45], v[160:163], v[192:195], v[42:45]
	v_mfma_f32_16x16x32_bf16 v[46:49], v[168:171], v[192:195], v[46:49]
	v_mfma_f32_16x16x32_bf16 v[58:61], v[160:163], v[200:203], v[58:61]
	v_mfma_f32_16x16x32_bf16 v[62:65], v[168:171], v[200:203], v[62:65]
	v_mfma_f32_16x16x32_bf16 v[10:13], v[164:167], v[180:183], v[10:13]
	v_mfma_f32_16x16x32_bf16 v[14:17], v[172:175], v[180:183], v[14:17]
	v_mfma_f32_16x16x32_bf16 v[26:29], v[164:167], v[188:191], v[26:29]
	v_mfma_f32_16x16x32_bf16 v[30:33], v[172:175], v[188:191], v[30:33]
	v_mfma_f32_16x16x32_bf16 v[42:45], v[164:167], v[196:199], v[42:45]
	v_mfma_f32_16x16x32_bf16 v[46:49], v[172:175], v[196:199], v[46:49]
	v_mfma_f32_16x16x32_bf16 v[58:61], v[164:167], v[204:207], v[58:61]
	v_mfma_f32_16x16x32_bf16 v[62:65], v[172:175], v[204:207], v[62:65]
	s_setprio 0
	s_barrier
	s_add_i32 s2, s74, s57
	v_lshl_add_u64 v[140:141], s[46:47], 0, v[130:131]
	s_mov_b32 m0, s2
	ds_read_b128 v[176:179], v139 offset:16384
	ds_read_b128 v[180:183], v139 offset:17408
	ds_read_b128 v[184:187], v139 offset:18432
	ds_read_b128 v[188:191], v139 offset:19456
	ds_read_b128 v[192:195], v139 offset:20480
	ds_read_b128 v[196:199], v139 offset:21504
	ds_read_b128 v[200:203], v139 offset:22528
	ds_read_b128 v[204:207], v139 offset:23552
	global_load_lds_dwordx4 v[140:141], off
	s_add_i32 m0, s2, 0x2000
	s_add_u32 s82, s46, 0x40000
	v_lshl_add_u64 v[208:209], s[46:47], 0, v[132:133]
	s_addc_u32 s83, s47, 0
	s_add_i32 s2, s75, s57
	global_load_lds_dwordx4 v[208:209], off
	v_lshl_add_u64 v[210:211], s[82:83], 0, v[130:131]
	s_mov_b32 m0, s2
	v_lshl_add_u64 v[212:213], s[52:53], 0, v[132:133]
	global_load_lds_dwordx4 v[210:211], off
	v_lshl_add_u64 v[210:211], s[82:83], 0, v[132:133]
	s_add_i32 m0, s2, 0x2000
	s_nop 0
	global_load_lds_dwordx4 v[210:211], off
	v_lshl_add_u64 v[210:211], s[52:53], 0, v[130:131]
	s_mov_b32 m0, s64
	s_nop 0
	global_load_lds_dwordx4 v[210:211], off
	s_mov_b32 m0, s65
	s_nop 0
	global_load_lds_dwordx4 v[212:213], off
	s_waitcnt vmcnt(12)
	s_waitcnt lgkmcnt(0)
	s_barrier
; #define PG8_STAGE(bufoff, gbase, voff) do { _Pragma("unroll") for (int _i = 0; _i < 2; ++_i) \
;         __builtin_amdgcn_global_load_lds((const unsigned*)((const char*)(gbase) + (voff)[_i]), (PG8_LAS unsigned*)(lds + (bufoff) + ldsw + _i * 8192), 16, 0, 0); } while (0)
; #define PG8_LDA(dst, b, h) do { _Pragma("unroll") for (int m = 0; m < 4; ++m) _Pragma("unroll") for (int k = 0; k < 2; ++k) dst[m][k] = *(const PG8_LAS bf16x8*)(lds + PG8_SA(b, h) + aoff + m * 2048 + k * 1024); } while (0)
; #define PG8_LDB(dst, b, h) do { _Pragma("unroll") for (int n = 0; n < 2; ++n) _Pragma("unroll") for (int k = 0; k < 2; ++k) dst[n][k] = *(const PG8_LAS bf16x8*)(lds + PG8_SB(b, h) + boff + n * 2048 + k * 1024); } while (0)
; #define PG8_MMA(ai, bj, At, Bt) do { __builtin_amdgcn_s_setprio(1); _Pragma("unroll") for (int m = 0; m < 4; ++m) _Pragma("unroll") for (int n = 0; n < 2; ++n) _Pragma("unroll") for (int k = 0; k < 2; ++k) \
;         acc[ai][bj][m][n] = __builtin_amdgcn_mfma_f32_16x16x32_bf16(Bt[n][k], At[m][k], acc[ai][bj][m][n], 0, 0, 0); __builtin_amdgcn_s_setprio(0); } while (0)
; #define PG8_WAIT_V(n) asm volatile("s_waitcnt vmcnt(" #n ")" ::: "memory")
; #define PG8_WAIT_L(n) asm volatile("s_waitcnt lgkmcnt(" #n ")" ::: "memory")
; #define PG8_BAR __builtin_amdgcn_s_barrier()
; #define PG8_SCHED __builtin_amdgcn_sched_barrier(0)
; template <class Epi, class Sched, bool ALIGN_EPI = false, bool SP2 = false>
; __device__ __forceinline__ void gemm_phase(PG8_LAS unsigned char* lds, const Gemm g, const Sched& S, const Epi& E) {
;     ...
;             PG8_LDA(At, 0, 1); PG8_STAGE(PG8_SB(0, 0), b2, voffB); PG8_STAGE(PG8_SB(0, 1), b2 + hstep, voffB); PG8_STAGE(PG8_SA(0, 0), a2, voffA);
;             PG8_WAIT_V(8); PG8_WAIT_L(0); PG8_BAR; PG8_MMA(1, 0, At, B0); PG8_MMA(1, 1, At, B1); PG8_BAR; PG8_SCHED;
;             PG8_LDB(B0, 1, 0); PG8_LDB(B1, 1, 1); PG8_SCHED; PG8_LDA(At, 1, 0); PG8_STAGE(PG8_SA(0, 1), a2 + hstep, voffA);
;             PG8_WAIT_V(8); PG8_WAIT_L(0); PG8_BAR; PG8_MMA(0, 0, At, B0); PG8_MMA(0, 1, At, B1); PG8_BAR; PG8_SCHED;
	s_setprio 1
	s_waitcnt lgkmcnt(0)
	v_mfma_f32_16x16x32_bf16 v[70:73], v[144:147], v[176:179], v[70:73]
	v_mfma_f32_16x16x32_bf16 v[66:69], v[152:155], v[176:179], v[66:69]
	v_mfma_f32_16x16x32_bf16 v[86:89], v[144:147], v[184:187], v[86:89]
	v_mfma_f32_16x16x32_bf16 v[82:85], v[152:155], v[184:187], v[82:85]
	v_mfma_f32_16x16x32_bf16 v[102:105], v[144:147], v[192:195], v[102:105]
	v_mfma_f32_16x16x32_bf16 v[98:101], v[152:155], v[192:195], v[98:101]
	v_mfma_f32_16x16x32_bf16 v[118:121], v[144:147], v[200:203], v[118:121]
	v_mfma_f32_16x16x32_bf16 v[114:117], v[152:155], v[200:203], v[114:117]
	v_mfma_f32_16x16x32_bf16 v[70:73], v[148:151], v[180:183], v[70:73]
	v_mfma_f32_16x16x32_bf16 v[66:69], v[156:159], v[180:183], v[66:69]
	v_mfma_f32_16x16x32_bf16 v[86:89], v[148:151], v[188:191], v[86:89]
	v_mfma_f32_16x16x32_bf16 v[82:85], v[156:159], v[188:191], v[82:85]
	v_mfma_f32_16x16x32_bf16 v[102:105], v[148:151], v[196:199], v[102:105]
	v_mfma_f32_16x16x32_bf16 v[98:101], v[156:159], v[196:199], v[98:101]
	v_mfma_f32_16x16x32_bf16 v[118:121], v[148:151], v[204:207], v[118:121]
	v_mfma_f32_16x16x32_bf16 v[114:117], v[156:159], v[204:207], v[114:117]
	v_mfma_f32_16x16x32_bf16 v[74:77], v[160:163], v[176:179], v[74:77]
	v_mfma_f32_16x16x32_bf16 v[78:81], v[168:171], v[176:179], v[78:81]
	v_mfma_f32_16x16x32_bf16 v[90:93], v[160:163], v[184:187], v[90:93]
	v_mfma_f32_16x16x32_bf16 v[94:97], v[168:171], v[184:187], v[94:97]
	v_mfma_f32_16x16x32_bf16 v[106:109], v[160:163], v[192:195], v[106:109]
	v_mfma_f32_16x16x32_bf16 v[110:113], v[168:171], v[192:195], v[110:113]
	v_mfma_f32_16x16x32_bf16 v[122:125], v[160:163], v[200:203], v[122:125]
	v_mfma_f32_16x16x32_bf16 v[126:129], v[168:171], v[200:203], v[126:129]
	v_mfma_f32_16x16x32_bf16 v[74:77], v[164:167], v[180:183], v[74:77]
	v_mfma_f32_16x16x32_bf16 v[78:81], v[172:175], v[180:183], v[78:81]
	v_mfma_f32_16x16x32_bf16 v[90:93], v[164:167], v[188:191], v[90:93]
	v_mfma_f32_16x16x32_bf16 v[94:97], v[172:175], v[188:191], v[94:97]
	v_mfma_f32_16x16x32_bf16 v[106:109], v[164:167], v[196:199], v[106:109]
	v_mfma_f32_16x16x32_bf16 v[110:113], v[172:175], v[196:199], v[110:113]
	v_mfma_f32_16x16x32_bf16 v[122:125], v[164:167], v[204:207], v[122:125]
	v_mfma_f32_16x16x32_bf16 v[126:129], v[172:175], v[204:207], v[126:129]
	s_setprio 0
	s_barrier
	s_add_i32 s2, 0, 0x18000
	s_add_i32 s81, 0, 0x1c000
	v_add_u32_e32 v156, s2, v138
	v_add_u32_e32 v172, s81, v138
	ds_read_b128 v[144:147], v156
	ds_read_b128 v[148:151], v156 offset:1024
	ds_read_b128 v[152:155], v156 offset:2048
	ds_read_b128 v[156:159], v156 offset:3072
	ds_read_b128 v[160:163], v172
	ds_read_b128 v[164:167], v172 offset:1024
	ds_read_b128 v[168:171], v172 offset:2048
	ds_read_b128 v[172:175], v172 offset:3072
	s_add_u32 s52, s52, 0x40000
	s_addc_u32 s53, s53, 0
	s_mov_b32 m0, s66
	v_lshl_add_u64 v[214:215], s[52:53], 0, v[130:131]
	ds_read_b128 v[176:179], v139 offset:32768
	ds_read_b128 v[180:183], v139 offset:33792
	ds_read_b128 v[184:187], v139 offset:34816
	ds_read_b128 v[188:191], v139 offset:35840
	ds_read_b128 v[192:195], v139 offset:36864
	ds_read_b128 v[196:199], v139 offset:37888
	ds_read_b128 v[200:203], v139 offset:38912
	ds_read_b128 v[204:207], v139 offset:39936
	global_load_lds_dwordx4 v[214:215], off
	v_lshl_add_u64 v[214:215], s[52:53], 0, v[132:133]
	s_mov_b32 m0, s67
	s_nop 0
	global_load_lds_dwordx4 v[214:215], off
	s_waitcnt vmcnt(8)
	s_waitcnt lgkmcnt(0)
	s_barrier
; #define PG8_STAGE(bufoff, gbase, voff) do { _Pragma("unroll") for (int _i = 0; _i < 2; ++_i) \
;         __builtin_amdgcn_global_load_lds((const unsigned*)((const char*)(gbase) + (voff)[_i]), (PG8_LAS unsigned*)(lds + (bufoff) + ldsw + _i * 8192), 16, 0, 0); } while (0)
; #define PG8_LDA(dst, b, h) do { _Pragma("unroll") for (int m = 0; m < 4; ++m) _Pragma("unroll") for (int k = 0; k < 2; ++k) dst[m][k] = *(const PG8_LAS bf16x8*)(lds + PG8_SA(b, h) + aoff + m * 2048 + k * 1024); } while (0)
; #define PG8_LDB(dst, b, h) do { _Pragma("unroll") for (int n = 0; n < 2; ++n) _Pragma("unroll") for (int k = 0; k < 2; ++k) dst[n][k] = *(const PG8_LAS bf16x8*)(lds + PG8_SB(b, h) + boff + n * 2048 + k * 1024); } while (0)
; #define PG8_WAIT_V(n) asm volatile("s_waitcnt vmcnt(" #n ")" ::: "memory")
; #define PG8_WAIT_L(n) asm volatile("s_waitcnt lgkmcnt(" #n ")" ::: "memory")
; #define PG8_BAR __builtin_amdgcn_s_barrier()
; #define PG8_SCHED __builtin_amdgcn_sched_barrier(0)
;     __device__ __forceinline__ void init(f32x4 (&acc)[2][2][4][2], const Unit& u, int wr, int wc, int fr, int fq) const {
;     ...
;             for (int m = 0; m < 4; ++m) { const size_t off = ((size_t)u.pm * 256 + 128 * ai + 64 * wr + 16 * m + fr) * DM + u.pn * 256 + 32 * wc + 4 * fq;
; #pragma unroll
;                 for (int bj = 0; bj < 2; ++bj)
; #pragma unroll
;                     for (int n = 0; n < 2; ++n) acc[ai][bj][m][n] = __builtin_nontemporal_load((const f32x4*)(x + off + bj * HALF + n * 16)); }
; template <class Epi, class Sched, bool ALIGN_EPI = false, bool SP2 = false>
; __device__ __forceinline__ void gemm_phase(PG8_LAS unsigned char* lds, const Gemm g, const Sched& S, const Epi& E) {
;     ...
;             PG8_LDA(At, 0, 1); PG8_STAGE(PG8_SB(0, 0), b2, voffB); PG8_STAGE(PG8_SB(0, 1), b2 + hstep, voffB); PG8_STAGE(PG8_SA(0, 0), a2, voffA);
;             PG8_WAIT_V(8); PG8_WAIT_L(0); PG8_BAR; PG8_MMA(1, 0, At, B0); PG8_MMA(1, 1, At, B1); PG8_BAR; PG8_SCHED;
;             PG8_LDB(B0, 1, 0); PG8_LDB(B1, 1, 1); PG8_SCHED; PG8_LDA(At, 1, 0); PG8_STAGE(PG8_SA(0, 1), a2 + hstep, voffA);
;             PG8_WAIT_V(8); PG8_WAIT_L(0); PG8_BAR; PG8_MMA(0, 0, At, B0); PG8_MMA(0, 1, At, B1); PG8_BAR; PG8_SCHED;
;             PG8_LDA(At, 1, 1); PG8_STAGE(PG8_SB(1, 0), b3, voffB); PG8_STAGE(PG8_SB(1, 1), b3 + hstep, voffB); PG8_STAGE(PG8_SA(1, 0), a3, voffA);
	s_setprio 1
	s_waitcnt lgkmcnt(0)
	v_mfma_f32_16x16x32_bf16 v[2:5], v[144:147], v[176:179], v[2:5]
	v_mfma_f32_16x16x32_bf16 v[6:9], v[152:155], v[176:179], v[6:9]
	v_mfma_f32_16x16x32_bf16 v[22:25], v[144:147], v[184:187], v[22:25]
	v_mfma_f32_16x16x32_bf16 v[18:21], v[152:155], v[184:187], v[18:21]
	v_mfma_f32_16x16x32_bf16 v[38:41], v[144:147], v[192:195], v[38:41]
	v_mfma_f32_16x16x32_bf16 v[34:37], v[152:155], v[192:195], v[34:37]
	v_mfma_f32_16x16x32_bf16 v[54:57], v[144:147], v[200:203], v[54:57]
	v_mfma_f32_16x16x32_bf16 v[50:53], v[152:155], v[200:203], v[50:53]
	v_mfma_f32_16x16x32_bf16 v[2:5], v[148:151], v[180:183], v[2:5]
	v_mfma_f32_16x16x32_bf16 v[6:9], v[156:159], v[180:183], v[6:9]
	v_mfma_f32_16x16x32_bf16 v[22:25], v[148:151], v[188:191], v[22:25]
	v_mfma_f32_16x16x32_bf16 v[18:21], v[156:159], v[188:191], v[18:21]
	v_mfma_f32_16x16x32_bf16 v[38:41], v[148:151], v[196:199], v[38:41]
	v_mfma_f32_16x16x32_bf16 v[34:37], v[156:159], v[196:199], v[34:37]
	v_mfma_f32_16x16x32_bf16 v[54:57], v[148:151], v[204:207], v[54:57]
	v_mfma_f32_16x16x32_bf16 v[50:53], v[156:159], v[204:207], v[50:53]
	v_mfma_f32_16x16x32_bf16 v[10:13], v[160:163], v[176:179], v[10:13]
	v_mfma_f32_16x16x32_bf16 v[14:17], v[168:171], v[176:179], v[14:17]
	v_mfma_f32_16x16x32_bf16 v[26:29], v[160:163], v[184:187], v[26:29]
	v_mfma_f32_16x16x32_bf16 v[30:33], v[168:171], v[184:187], v[30:33]
	v_mfma_f32_16x16x32_bf16 v[42:45], v[160:163], v[192:195], v[42:45]
	v_mfma_f32_16x16x32_bf16 v[46:49], v[168:171], v[192:195], v[46:49]
	v_mfma_f32_16x16x32_bf16 v[58:61], v[160:163], v[200:203], v[58:61]
	v_mfma_f32_16x16x32_bf16 v[62:65], v[168:171], v[200:203], v[62:65]
	v_mfma_f32_16x16x32_bf16 v[10:13], v[164:167], v[180:183], v[10:13]
	v_mfma_f32_16x16x32_bf16 v[14:17], v[172:175], v[180:183], v[14:17]
	v_mfma_f32_16x16x32_bf16 v[26:29], v[164:167], v[188:191], v[26:29]
	v_mfma_f32_16x16x32_bf16 v[30:33], v[172:175], v[188:191], v[30:33]
	v_mfma_f32_16x16x32_bf16 v[42:45], v[164:167], v[196:199], v[42:45]
	v_mfma_f32_16x16x32_bf16 v[46:49], v[172:175], v[196:199], v[46:49]
	v_mfma_f32_16x16x32_bf16 v[58:61], v[164:167], v[204:207], v[58:61]
	v_mfma_f32_16x16x32_bf16 v[62:65], v[172:175], v[204:207], v[62:65]
	s_setprio 0
	s_barrier
	s_add_i32 s2, s2, s57
	v_lshl_add_u64 v[140:141], v[140:141], 0, s[26:27]
	s_mov_b32 m0, s2
	ds_read_b128 v[176:179], v139 offset:49152
	ds_read_b128 v[180:183], v139 offset:50176
	ds_read_b128 v[184:187], v139 offset:51200
	ds_read_b128 v[188:191], v139 offset:52224
	ds_read_b128 v[192:195], v139 offset:53248
	ds_read_b128 v[196:199], v139 offset:54272
	ds_read_b128 v[200:203], v139 offset:55296
	ds_read_b128 v[204:207], v139 offset:56320
	global_load_lds_dwordx4 v[140:141], off
	s_add_i32 m0, s2, 0x2000
	s_add_u32 s46, s46, 0x40080
	v_lshl_add_u64 v[140:141], v[208:209], 0, s[26:27]
	s_addc_u32 s47, s47, 0
	s_add_i32 s2, s81, s57
	global_load_lds_dwordx4 v[140:141], off
	v_lshl_add_u64 v[140:141], s[46:47], 0, v[130:131]
	s_mov_b32 m0, s2
	s_nop 0
	global_load_lds_dwordx4 v[140:141], off
	v_lshl_add_u64 v[140:141], s[46:47], 0, v[132:133]
	s_add_i32 m0, s2, 0x2000
	s_nop 0
	global_load_lds_dwordx4 v[140:141], off
	v_lshl_add_u64 v[140:141], v[210:211], 0, s[26:27]
	s_mov_b32 m0, s68
	s_nop 0
	global_load_lds_dwordx4 v[140:141], off
	v_lshl_add_u64 v[140:141], v[212:213], 0, s[26:27]
	s_mov_b32 m0, s69
	s_nop 0
	global_load_lds_dwordx4 v[140:141], off
	s_cmp_lt_i32 s80, 6
	s_cbranch_scc0 .Lxa_hi
	s_cmp_lt_i32 s80, 2
	s_cbranch_scc0 .Lxa_23
	s_cmp_lt_i32 s80, 0
	s_cbranch_scc0 .Lxa_1
	v_add_f32_e32 v2, v2, v216
	v_add_f32_e32 v3, v3, v217
	v_add_f32_e32 v4, v4, v218
	v_add_f32_e32 v5, v5, v219
	v_add_f32_e32 v6, v6, v220
	v_add_f32_e32 v7, v7, v221
	v_add_f32_e32 v8, v8, v222
	v_add_f32_e32 v9, v9, v223
	v_add_f32_e32 v10, v10, v224
	v_add_f32_e32 v11, v11, v225
	v_add_f32_e32 v12, v12, v226
	v_add_f32_e32 v13, v13, v227
	v_add_f32_e32 v14, v14, v228
	v_add_f32_e32 v15, v15, v229
	v_add_f32_e32 v16, v16, v230
	v_add_f32_e32 v17, v17, v231
	s_branch .Lxa_done

; #define PG8_STAGE(bufoff, gbase, voff) do { _Pragma("unroll") for (int _i = 0; _i < 2; ++_i) \
;         __builtin_amdgcn_global_load_lds((const unsigned*)((const char*)(gbase) + (voff)[_i]), (PG8_LAS unsigned*)(lds + (bufoff) + ldsw + _i * 8192), 16, 0, 0); } while (0)
; #define PG8_LDA(dst, b, h) do { _Pragma("unroll") for (int m = 0; m < 4; ++m) _Pragma("unroll") for (int k = 0; k < 2; ++k) dst[m][k] = *(const PG8_LAS bf16x8*)(lds + PG8_SA(b, h) + aoff + m * 2048 + k * 1024); } while (0)
; #define PG8_MMA(ai, bj, At, Bt) do { __builtin_amdgcn_s_setprio(1); _Pragma("unroll") for (int m = 0; m < 4; ++m) _Pragma("unroll") for (int n = 0; n < 2; ++n) _Pragma("unroll") for (int k = 0; k < 2; ++k) \
;         acc[ai][bj][m][n] = __builtin_amdgcn_mfma_f32_16x16x32_bf16(Bt[n][k], At[m][k], acc[ai][bj][m][n], 0, 0, 0); __builtin_amdgcn_s_setprio(0); } while (0)
; #define PG8_WAIT_V(n) asm volatile("s_waitcnt vmcnt(" #n ")" ::: "memory")
; #define PG8_WAIT_L(n) asm volatile("s_waitcnt lgkmcnt(" #n ")" ::: "memory")
; #define PG8_BAR __builtin_amdgcn_s_barrier()
; #define PG8_SCHED __builtin_amdgcn_sched_barrier(0)
; template <class Epi, class Sched, bool ALIGN_EPI = false, bool SP2 = false>
; __device__ __forceinline__ void gemm_phase(PG8_LAS unsigned char* lds, const Gemm g, const Sched& S, const Epi& E) {
;     ...
;         for (int t = 0; t < nt; t += 2) {
;             if constexpr (Epi::HAS_MID) { if (t == nt / 2) E.mid(acc, cur, wr, wc, fr, fq); }
;             const bool last = (t == nt - 2);
;             const char* a1 = cA + (size_t)(t + 1) * kstep;
;             const char* a2 = last ? nA : cA + (size_t)(t + 2) * kstep; const char* b2 = last ? nB : cB + (size_t)(t + 2) * kstep;
;             const char* a3 = a2 + kstep; const char* b3 = b2 + kstep;
;     ...
;             PG8_LDA(At, 1, 1); PG8_STAGE(PG8_SB(1, 0), b3, voffB); PG8_STAGE(PG8_SB(1, 1), b3 + hstep, voffB); PG8_STAGE(PG8_SA(1, 0), a3, voffA);
;             PG8_WAIT_V(8); PG8_WAIT_L(0); PG8_BAR; PG8_MMA(1, 0, At, B0); PG8_MMA(1, 1, At, B1); PG8_BAR; PG8_SCHED;
.Lxa_done:
	s_add_i32 s92, s80, 4
	s_and_b32 s93, s92, 6
	s_lshl_b32 s93, s93, 15
	s_and_b32 s92, s92, 8
	s_lshl_b32 s92, s92, 16
	s_add_i32 s92, s92, s93
	s_cmp_eq_u32 s80, 12
	s_cselect_b32 s90, s86, s84
	s_cselect_b32 s91, s87, s85
	s_add_u32 s90, s90, s92
	s_addc_u32 s91, s91, 0
	v_lshl_add_u64 v[232:233], v[234:235], 0, s[90:91]
	global_load_dwordx4 v[216:219], v[232:233], off nt
	global_load_dwordx4 v[220:223], v[232:233], off offset:64 nt
	global_load_dwordx4 v[224:227], v[232:233], off offset:512 nt
	global_load_dwordx4 v[228:231], v[232:233], off offset:576 nt
	s_waitcnt vmcnt(12)
	s_waitcnt lgkmcnt(0)
	s_barrier
	s_setprio 1
	s_waitcnt lgkmcnt(0)
	v_mfma_f32_16x16x32_bf16 v[70:73], v[144:147], v[176:179], v[70:73]
	v_mfma_f32_16x16x32_bf16 v[66:69], v[152:155], v[176:179], v[66:69]
	v_mfma_f32_16x16x32_bf16 v[86:89], v[144:147], v[184:187], v[86:89]
	v_mfma_f32_16x16x32_bf16 v[82:85], v[152:155], v[184:187], v[82:85]
	v_mfma_f32_16x16x32_bf16 v[102:105], v[144:147], v[192:195], v[102:105]
	v_mfma_f32_16x16x32_bf16 v[98:101], v[152:155], v[192:195], v[98:101]
	v_mfma_f32_16x16x32_bf16 v[118:121], v[144:147], v[200:203], v[118:121]
	v_mfma_f32_16x16x32_bf16 v[114:117], v[152:155], v[200:203], v[114:117]
	v_mfma_f32_16x16x32_bf16 v[70:73], v[148:151], v[180:183], v[70:73]
	v_mfma_f32_16x16x32_bf16 v[66:69], v[156:159], v[180:183], v[66:69]
	v_mfma_f32_16x16x32_bf16 v[86:89], v[148:151], v[188:191], v[86:89]
	v_mfma_f32_16x16x32_bf16 v[82:85], v[156:159], v[188:191], v[82:85]
	v_mfma_f32_16x16x32_bf16 v[102:105], v[148:151], v[196:199], v[102:105]
	v_mfma_f32_16x16x32_bf16 v[98:101], v[156:159], v[196:199], v[98:101]
	v_mfma_f32_16x16x32_bf16 v[118:121], v[148:151], v[204:207], v[118:121]
	v_mfma_f32_16x16x32_bf16 v[114:117], v[156:159], v[204:207], v[114:117]
	v_mfma_f32_16x16x32_bf16 v[74:77], v[160:163], v[176:179], v[74:77]
	v_mfma_f32_16x16x32_bf16 v[78:81], v[168:171], v[176:179], v[78:81]
	v_mfma_f32_16x16x32_bf16 v[90:93], v[160:163], v[184:187], v[90:93]
	v_mfma_f32_16x16x32_bf16 v[94:97], v[168:171], v[184:187], v[94:97]
	v_mfma_f32_16x16x32_bf16 v[106:109], v[160:163], v[192:195], v[106:109]
	v_mfma_f32_16x16x32_bf16 v[110:113], v[168:171], v[192:195], v[110:113]
	v_mfma_f32_16x16x32_bf16 v[122:125], v[160:163], v[200:203], v[122:125]
	v_mfma_f32_16x16x32_bf16 v[126:129], v[168:171], v[200:203], v[126:129]
	v_mfma_f32_16x16x32_bf16 v[74:77], v[164:167], v[180:183], v[74:77]
	v_mfma_f32_16x16x32_bf16 v[78:81], v[172:175], v[180:183], v[78:81]
	v_mfma_f32_16x16x32_bf16 v[90:93], v[164:167], v[188:191], v[90:93]
	v_mfma_f32_16x16x32_bf16 v[94:97], v[172:175], v[188:191], v[94:97]
	v_mfma_f32_16x16x32_bf16 v[106:109], v[164:167], v[196:199], v[106:109]
	v_mfma_f32_16x16x32_bf16 v[110:113], v[172:175], v[196:199], v[110:113]
	v_mfma_f32_16x16x32_bf16 v[122:125], v[164:167], v[204:207], v[122:125]
	v_mfma_f32_16x16x32_bf16 v[126:129], v[172:175], v[204:207], v[126:129]
	s_setprio 0
	s_barrier
	s_add_i32 s80, s80, 2
	s_add_u32 s48, s48, 0x100
	s_addc_u32 s49, s49, 0
	s_add_u32 s78, s78, 0x100
	s_addc_u32 s79, s79, 0
	s_cmp_gt_u32 s80, 13
	s_cbranch_scc0 .LBB0_722
	s_and_b64 vcc, exec, s[34:35]
	s_cbranch_vccz .LBB0_725
	s_barrier
